# grid-barrier spins back off with s_sleep 4 between polls of the arrival counter (less traffic on that word)
# speedup vs baseline: 1.0060x; 1.0060x over previous
.LBB0_18:
	s_sleep 4
	global_load_dword v2, v0, s[4:5] offset:32 sc1
	s_waitcnt vmcnt(0)
	v_and_b32_e32 v2, 0xffff0000, v2
	v_cmp_ne_u32_e32 vcc, v2, v1
	s_or_b64 s[6:7], vcc, s[6:7]
	s_andn2_b64 exec, exec, s[6:7]
	s_cbranch_execnz .LBB0_18

.LBB0_84:
	global_load_dword v15, v16, s[78:79] offset:1024 sc1
	s_waitcnt lgkmcnt(0)
	global_load_dword v0, v16, s[78:79] offset:1280 sc1
	global_load_dword v1, v16, s[78:79] offset:1536 sc1
	global_load_dword v2, v16, s[78:79] offset:1792 sc1
	global_load_dword v3, v16, s[78:79] offset:2048 sc1
	global_load_dword v4, v16, s[78:79] offset:2304 sc1
	global_load_dword v5, v16, s[78:79] offset:2560 sc1
	global_load_dword v6, v16, s[78:79] offset:2816 sc1
	global_load_dword v7, v16, s[78:79] offset:3072 sc1
	global_load_dword v8, v16, s[78:79] offset:3328 sc1
	global_load_dword v9, v16, s[78:79] offset:3584 sc1
	global_load_dword v10, v16, s[78:79] offset:3840 sc1
	global_load_dword v11, v16, s[6:7] sc1
	global_load_dword v12, v16, s[8:9] sc1
	global_load_dword v13, v16, s[10:11] sc1
	global_load_dword v14, v16, s[12:13] sc1
	s_mov_b64 s[14:15], -1
	s_mov_b64 s[16:17], -1
	s_waitcnt vmcnt(14)
	v_add_u32_e32 v17, v0, v15
	s_waitcnt vmcnt(13)
	v_add_u32_e32 v17, v17, v1
	s_waitcnt vmcnt(12)
	v_add_u32_e32 v17, v17, v2
	s_waitcnt vmcnt(11)
	v_add_u32_e32 v17, v17, v3
	s_waitcnt vmcnt(10)
	v_add_u32_e32 v17, v17, v4
	s_waitcnt vmcnt(9)
	v_add_u32_e32 v17, v17, v5
	s_waitcnt vmcnt(8)
	v_add_u32_e32 v17, v17, v6
	s_waitcnt vmcnt(7)
	v_add_u32_e32 v17, v17, v7
	s_waitcnt vmcnt(6)
	v_add_u32_e32 v17, v17, v8
	s_waitcnt vmcnt(5)
	v_add_u32_e32 v17, v17, v9
	s_waitcnt vmcnt(4)
	v_add_u32_e32 v17, v17, v10
	s_waitcnt vmcnt(3)
	v_add_u32_e32 v17, v17, v11
	s_waitcnt vmcnt(2)
	v_add_u32_e32 v17, v17, v12
	s_waitcnt vmcnt(1)
	v_add_u32_e32 v17, v17, v13
	s_waitcnt vmcnt(0)
	v_add_u32_e32 v17, v17, v14
	v_cmp_eq_u32_e32 vcc, s3, v17
	s_cbranch_vccnz .LBB0_83
	s_and_b32 s14, s20, 0xff
	s_cmp_eq_u32 s14, 0
	s_mov_b64 s[14:15], -1
	s_mov_b64 s[18:19], -1
	s_sleep 4
	s_cbranch_scc0 .LBB0_88
	global_load_dword v17, v16, s[78:79] offset:512 sc1
	s_waitcnt vmcnt(0)
	v_cmp_eq_u32_e32 vcc, 0, v17
	s_cbranch_vccnz .LBB0_90
	s_mov_b64 s[18:19], 0

.LBB0_102:
	s_and_b32 s20, s3, 0xff
	s_mov_b64 s[18:19], -1
	s_cmp_lg_u32 s20, 0
	s_mov_b64 s[22:23], -1
	s_sleep 4
	s_cbranch_scc1 .LBB0_105
	global_load_dword v2, v0, s[78:79] offset:512 sc1
	s_waitcnt vmcnt(0)
	v_cmp_eq_u32_e32 vcc, 0, v2
	s_cbranch_vccnz .LBB0_107
	s_mov_b64 s[22:23], 0
	s_mov_b64 s[20:21], -1

.LBB0_119:
	s_and_b32 s20, s3, 0xff
	s_cmp_lg_u32 s20, 0
	s_mov_b64 s[22:23], -1
	s_sleep 4
	s_cbranch_scc1 .LBB0_122
	global_load_dword v1, v0, s[12:13] sc1
	s_waitcnt vmcnt(0)
	v_cmp_eq_u32_e32 vcc, 0, v1
	s_cbranch_vccnz .LBB0_124
	s_mov_b64 s[22:23], 0
	s_mov_b64 s[20:21], -1

.LBB0_157:
	global_load_dword v15, v16, s[78:79] offset:1024 sc1
	s_waitcnt lgkmcnt(0)
	global_load_dword v0, v16, s[78:79] offset:1280 sc1
	global_load_dword v1, v16, s[78:79] offset:1536 sc1
	global_load_dword v2, v16, s[78:79] offset:1792 sc1
	global_load_dword v3, v16, s[78:79] offset:2048 sc1
	global_load_dword v4, v16, s[78:79] offset:2304 sc1
	global_load_dword v5, v16, s[78:79] offset:2560 sc1
	global_load_dword v6, v16, s[78:79] offset:2816 sc1
	global_load_dword v7, v16, s[78:79] offset:3072 sc1
	global_load_dword v8, v16, s[78:79] offset:3328 sc1
	global_load_dword v9, v16, s[78:79] offset:3584 sc1
	global_load_dword v10, v16, s[78:79] offset:3840 sc1
	global_load_dword v11, v16, s[4:5] sc1
	global_load_dword v12, v16, s[6:7] sc1
	global_load_dword v13, v16, s[8:9] sc1
	global_load_dword v14, v16, s[10:11] sc1
	s_mov_b64 s[12:13], -1
	s_mov_b64 s[14:15], -1
	s_waitcnt vmcnt(14)
	v_add_u32_e32 v17, v0, v15
	s_waitcnt vmcnt(13)
	v_add_u32_e32 v17, v17, v1
	s_waitcnt vmcnt(12)
	v_add_u32_e32 v17, v17, v2
	s_waitcnt vmcnt(11)
	v_add_u32_e32 v17, v17, v3
	s_waitcnt vmcnt(10)
	v_add_u32_e32 v17, v17, v4
	s_waitcnt vmcnt(9)
	v_add_u32_e32 v17, v17, v5
	s_waitcnt vmcnt(8)
	v_add_u32_e32 v17, v17, v6
	s_waitcnt vmcnt(7)
	v_add_u32_e32 v17, v17, v7
	s_waitcnt vmcnt(6)
	v_add_u32_e32 v17, v17, v8
	s_waitcnt vmcnt(5)
	v_add_u32_e32 v17, v17, v9
	s_waitcnt vmcnt(4)
	v_add_u32_e32 v17, v17, v10
	s_waitcnt vmcnt(3)
	v_add_u32_e32 v17, v17, v11
	s_waitcnt vmcnt(2)
	v_add_u32_e32 v17, v17, v12
	s_waitcnt vmcnt(1)
	v_add_u32_e32 v17, v17, v13
	s_waitcnt vmcnt(0)
	v_add_u32_e32 v17, v17, v14
	v_cmp_eq_u32_e32 vcc, s18, v17
	s_cbranch_vccnz .LBB0_156
	s_and_b32 s12, s19, 0xff
	s_cmp_eq_u32 s12, 0
	s_mov_b64 s[12:13], -1
	s_mov_b64 s[16:17], -1
	s_sleep 4
	s_cbranch_scc0 .LBB0_161
	global_load_dword v17, v16, s[78:79] offset:512 sc1
	s_waitcnt vmcnt(0)
	v_cmp_eq_u32_e32 vcc, 0, v17
	s_cbranch_vccnz .LBB0_163
	s_mov_b64 s[16:17], 0

.LBB0_175:
	s_and_b32 s18, s22, 0xff
	s_mov_b64 s[16:17], -1
	s_cmp_lg_u32 s18, 0
	s_mov_b64 s[20:21], -1
	s_sleep 4
	s_cbranch_scc1 .LBB0_178
	global_load_dword v2, v0, s[78:79] offset:512 sc1
	s_waitcnt vmcnt(0)
	v_cmp_eq_u32_e32 vcc, 0, v2
	s_cbranch_vccnz .LBB0_180
	s_mov_b64 s[20:21], 0
	s_mov_b64 s[18:19], -1

.LBB0_192:
	s_and_b32 s18, s26, 0xff
	s_cmp_lg_u32 s18, 0
	s_mov_b64 s[20:21], -1
	s_sleep 4
	s_cbranch_scc1 .LBB0_195
	global_load_dword v1, v0, s[10:11] sc1
	s_waitcnt vmcnt(0)
	v_cmp_eq_u32_e32 vcc, 0, v1
	s_cbranch_vccnz .LBB0_197
	s_mov_b64 s[20:21], 0
	s_mov_b64 s[18:19], -1

.LBB0_505:
	s_and_b32 s18, s24, 0xff
	s_cmp_lg_u32 s18, 0
	s_mov_b64 s[20:21], -1
	s_sleep 4
	s_cbranch_scc1 .LBB0_508
	global_load_dword v1, v0, s[10:11] sc1
	s_waitcnt vmcnt(0)
	v_cmp_eq_u32_e32 vcc, 0, v1
	s_cbranch_vccnz .LBB0_510
	s_mov_b64 s[20:21], 0
	s_mov_b64 s[18:19], -1

.LBB0_1272:
	global_load_dword v15, v16, s[78:79] offset:1024 sc1
	s_waitcnt lgkmcnt(0)
	global_load_dword v0, v16, s[78:79] offset:1280 sc1
	global_load_dword v1, v16, s[78:79] offset:1536 sc1
	global_load_dword v2, v16, s[78:79] offset:1792 sc1
	global_load_dword v3, v16, s[78:79] offset:2048 sc1
	global_load_dword v4, v16, s[78:79] offset:2304 sc1
	global_load_dword v5, v16, s[78:79] offset:2560 sc1
	global_load_dword v6, v16, s[78:79] offset:2816 sc1
	global_load_dword v7, v16, s[78:79] offset:3072 sc1
	global_load_dword v8, v16, s[78:79] offset:3328 sc1
	global_load_dword v9, v16, s[78:79] offset:3584 sc1
	global_load_dword v10, v16, s[78:79] offset:3840 sc1
	global_load_dword v11, v16, s[6:7] sc1
	global_load_dword v12, v16, s[8:9] sc1
	global_load_dword v13, v16, s[10:11] sc1
	global_load_dword v14, v16, s[12:13] sc1
	s_mov_b64 s[14:15], -1
	s_mov_b64 s[16:17], -1
	s_waitcnt vmcnt(14)
	v_add_u32_e32 v17, v0, v15
	s_waitcnt vmcnt(13)
	v_add_u32_e32 v17, v17, v1
	s_waitcnt vmcnt(12)
	v_add_u32_e32 v17, v17, v2
	s_waitcnt vmcnt(11)
	v_add_u32_e32 v17, v17, v3
	s_waitcnt vmcnt(10)
	v_add_u32_e32 v17, v17, v4
	s_waitcnt vmcnt(9)
	v_add_u32_e32 v17, v17, v5
	s_waitcnt vmcnt(8)
	v_add_u32_e32 v17, v17, v6
	s_waitcnt vmcnt(7)
	v_add_u32_e32 v17, v17, v7
	s_waitcnt vmcnt(6)
	v_add_u32_e32 v17, v17, v8
	s_waitcnt vmcnt(5)
	v_add_u32_e32 v17, v17, v9
	s_waitcnt vmcnt(4)
	v_add_u32_e32 v17, v17, v10
	s_waitcnt vmcnt(3)
	v_add_u32_e32 v17, v17, v11
	s_waitcnt vmcnt(2)
	v_add_u32_e32 v17, v17, v12
	s_waitcnt vmcnt(1)
	v_add_u32_e32 v17, v17, v13
	s_waitcnt vmcnt(0)
	v_add_u32_e32 v17, v17, v14
	v_cmp_eq_u32_e32 vcc, s20, v17
	s_cbranch_vccnz .LBB0_1271
	s_and_b32 s14, s21, 0xff
	s_cmp_eq_u32 s14, 0
	s_mov_b64 s[14:15], -1
	s_mov_b64 s[18:19], -1
	s_sleep 4
	s_cbranch_scc0 .LBB0_1276
	global_load_dword v17, v16, s[78:79] offset:512 sc1
	s_waitcnt vmcnt(0)
	v_cmp_eq_u32_e32 vcc, 0, v17
	s_cbranch_vccnz .LBB0_1278
	s_mov_b64 s[18:19], 0

.LBB0_1290:
	s_and_b32 s20, s24, 0xff
	s_mov_b64 s[18:19], -1
	s_cmp_lg_u32 s20, 0
	s_mov_b64 s[22:23], -1
	s_sleep 4
	s_cbranch_scc1 .LBB0_1293
	global_load_dword v2, v0, s[78:79] offset:512 sc1
	s_waitcnt vmcnt(0)
	v_cmp_eq_u32_e32 vcc, 0, v2
	s_cbranch_vccnz .LBB0_1295
	s_mov_b64 s[22:23], 0
	s_mov_b64 s[20:21], -1

.LBB0_1307:
	s_and_b32 s20, s26, 0xff
	s_cmp_lg_u32 s20, 0
	s_mov_b64 s[22:23], -1
	s_sleep 4
	s_cbranch_scc1 .LBB0_1310
	global_load_dword v1, v0, s[12:13] sc1
	s_waitcnt vmcnt(0)
	v_cmp_eq_u32_e32 vcc, 0, v1
	s_cbranch_vccnz .LBB0_1312
	s_mov_b64 s[22:23], 0
	s_mov_b64 s[20:21], -1

.LBB0_2691:
	global_load_dword v15, v16, s[78:79] offset:1024 sc1
	s_waitcnt lgkmcnt(0)
	global_load_dword v0, v16, s[78:79] offset:1280 sc1
	global_load_dword v1, v16, s[78:79] offset:1536 sc1
	global_load_dword v2, v16, s[78:79] offset:1792 sc1
	global_load_dword v3, v16, s[78:79] offset:2048 sc1
	global_load_dword v4, v16, s[78:79] offset:2304 sc1
	global_load_dword v5, v16, s[78:79] offset:2560 sc1
	global_load_dword v6, v16, s[78:79] offset:2816 sc1
	global_load_dword v7, v16, s[78:79] offset:3072 sc1
	global_load_dword v8, v16, s[78:79] offset:3328 sc1
	global_load_dword v9, v16, s[78:79] offset:3584 sc1
	global_load_dword v10, v16, s[78:79] offset:3840 sc1
	global_load_dword v11, v16, s[4:5] sc1
	global_load_dword v12, v16, s[6:7] sc1
	global_load_dword v13, v16, s[10:11] sc1
	global_load_dword v14, v16, s[12:13] sc1
	s_mov_b64 s[14:15], -1
	s_mov_b64 s[16:17], -1
	s_waitcnt vmcnt(14)
	v_add_u32_e32 v17, v0, v15
	s_waitcnt vmcnt(13)
	v_add_u32_e32 v17, v17, v1
	s_waitcnt vmcnt(12)
	v_add_u32_e32 v17, v17, v2
	s_waitcnt vmcnt(11)
	v_add_u32_e32 v17, v17, v3
	s_waitcnt vmcnt(10)
	v_add_u32_e32 v17, v17, v4
	s_waitcnt vmcnt(9)
	v_add_u32_e32 v17, v17, v5
	s_waitcnt vmcnt(8)
	v_add_u32_e32 v17, v17, v6
	s_waitcnt vmcnt(7)
	v_add_u32_e32 v17, v17, v7
	s_waitcnt vmcnt(6)
	v_add_u32_e32 v17, v17, v8
	s_waitcnt vmcnt(5)
	v_add_u32_e32 v17, v17, v9
	s_waitcnt vmcnt(4)
	v_add_u32_e32 v17, v17, v10
	s_waitcnt vmcnt(3)
	v_add_u32_e32 v17, v17, v11
	s_waitcnt vmcnt(2)
	v_add_u32_e32 v17, v17, v12
	s_waitcnt vmcnt(1)
	v_add_u32_e32 v17, v17, v13
	s_waitcnt vmcnt(0)
	v_add_u32_e32 v17, v17, v14
	v_cmp_eq_u32_e32 vcc, s20, v17
	s_cbranch_vccnz .LBB0_2690
	s_and_b32 s14, s21, 0xff
	s_cmp_eq_u32 s14, 0
	s_mov_b64 s[14:15], -1
	s_mov_b64 s[18:19], -1
	s_sleep 4
	s_cbranch_scc0 .LBB0_2695
	global_load_dword v17, v16, s[78:79] offset:512 sc1
	s_waitcnt vmcnt(0)
	v_cmp_eq_u32_e32 vcc, 0, v17
	s_cbranch_vccnz .LBB0_2697
	s_mov_b64 s[18:19], 0

.LBB0_2800:
	global_load_dword v15, v16, s[78:79] offset:1024 sc1
	s_waitcnt lgkmcnt(0)
	global_load_dword v0, v16, s[78:79] offset:1280 sc1
	global_load_dword v1, v16, s[78:79] offset:1536 sc1
	global_load_dword v2, v16, s[78:79] offset:1792 sc1
	global_load_dword v3, v16, s[78:79] offset:2048 sc1
	global_load_dword v4, v16, s[78:79] offset:2304 sc1
	global_load_dword v5, v16, s[78:79] offset:2560 sc1
	global_load_dword v6, v16, s[78:79] offset:2816 sc1
	global_load_dword v7, v16, s[78:79] offset:3072 sc1
	global_load_dword v8, v16, s[78:79] offset:3328 sc1
	global_load_dword v9, v16, s[78:79] offset:3584 sc1
	global_load_dword v10, v16, s[78:79] offset:3840 sc1
	global_load_dword v11, v16, s[2:3] sc1
	global_load_dword v12, v16, s[4:5] sc1
	global_load_dword v13, v16, s[6:7] sc1
	global_load_dword v14, v16, s[8:9] sc1
	s_mov_b64 s[10:11], -1
	s_mov_b64 s[12:13], -1
	s_waitcnt vmcnt(14)
	v_add_u32_e32 v17, v0, v15
	s_waitcnt vmcnt(13)
	v_add_u32_e32 v17, v17, v1
	s_waitcnt vmcnt(12)
	v_add_u32_e32 v17, v17, v2
	s_waitcnt vmcnt(11)
	v_add_u32_e32 v17, v17, v3
	s_waitcnt vmcnt(10)
	v_add_u32_e32 v17, v17, v4
	s_waitcnt vmcnt(9)
	v_add_u32_e32 v17, v17, v5
	s_waitcnt vmcnt(8)
	v_add_u32_e32 v17, v17, v6
	s_waitcnt vmcnt(7)
	v_add_u32_e32 v17, v17, v7
	s_waitcnt vmcnt(6)
	v_add_u32_e32 v17, v17, v8
	s_waitcnt vmcnt(5)
	v_add_u32_e32 v17, v17, v9
	s_waitcnt vmcnt(4)
	v_add_u32_e32 v17, v17, v10
	s_waitcnt vmcnt(3)
	v_add_u32_e32 v17, v17, v11
	s_waitcnt vmcnt(2)
	v_add_u32_e32 v17, v17, v12
	s_waitcnt vmcnt(1)
	v_add_u32_e32 v17, v17, v13
	s_waitcnt vmcnt(0)
	v_add_u32_e32 v17, v17, v14
	v_cmp_eq_u32_e32 vcc, s16, v17
	s_cbranch_vccnz .LBB0_2799
	s_and_b32 s10, s17, 0xff
	s_cmp_eq_u32 s10, 0
	s_mov_b64 s[10:11], -1
	s_mov_b64 s[14:15], -1
	s_sleep 4
	s_cbranch_scc0 .LBB0_2804
	global_load_dword v17, v16, s[78:79] offset:512 sc1
	s_waitcnt vmcnt(0)
	v_cmp_eq_u32_e32 vcc, 0, v17
	s_cbranch_vccnz .LBB0_2806
	s_mov_b64 s[14:15], 0

.LBB0_2818:
	s_and_b32 s16, s20, 0xff
	s_mov_b64 s[14:15], -1
	s_cmp_lg_u32 s16, 0
	s_mov_b64 s[18:19], -1
	s_sleep 4
	s_cbranch_scc1 .LBB0_2821
	global_load_dword v2, v0, s[78:79] offset:512 sc1
	s_waitcnt vmcnt(0)
	v_cmp_eq_u32_e32 vcc, 0, v2
	s_cbranch_vccnz .LBB0_2823
	s_mov_b64 s[18:19], 0
	s_mov_b64 s[16:17], -1

.LBB0_2835:
	s_and_b32 s16, s22, 0xff
	s_cmp_lg_u32 s16, 0
	s_mov_b64 s[18:19], -1
	s_sleep 4
	s_cbranch_scc1 .LBB0_2838
	global_load_dword v1, v0, s[8:9] sc1
	s_waitcnt vmcnt(0)
	v_cmp_eq_u32_e32 vcc, 0, v1
	s_cbranch_vccnz .LBB0_2840
	s_mov_b64 s[18:19], 0
	s_mov_b64 s[16:17], -1
